# v149 + nt on the sa gate loads of the 4a transform and the sb gate loads of the 4a epilogue (last use)
# baseline (speedup 1.0000x reference)
.LBB0_552:
	s_or_b64 exec, exec, s[2:3]
	s_mov_b64 s[2:3], -1
	s_and_b64 vcc, exec, s[42:43]
	v_add_u32_e32 v145, 0x400, v219
	v_add_u32_e32 v144, 0x800, v219
	v_add_u32_e32 v143, 0xc00, v219
	v_add_u32_e32 v142, 0x4000, v219
	v_add_u32_e32 v141, 0x4400, v219
	v_add_u32_e32 v140, 0x4800, v219
	v_add_u32_e32 v139, 0x4c00, v219
	v_add_u32_e32 v147, 0x8000, v219
	v_add_u32_e32 v138, 0x8400, v219
	v_add_u32_e32 v136, 0x8800, v219
	v_add_u32_e32 v135, 0x8c00, v219
	v_add_u32_e32 v146, 0xc000, v219
	v_add_u32_e32 v134, 0xc400, v219
	v_add_u32_e32 v133, 0xc800, v219
	v_add_u32_e32 v132, 0xcc00, v219
	v_add_u32_e32 v137, 0x9000, v219
	v_add_u32_e32 v0, 0xd000, v219
	s_waitcnt vmcnt(0) lgkmcnt(0)
	s_cbranch_vccz .LBB0_559
	s_mov_b32 s2, 0
	v_mov_b32_e32 v2, v225
	s_barrier
	ds_write2_b32 v219, v68, v72 offset1:16
	ds_write2_b32 v145, v69, v73 offset0:4 offset1:20
	ds_write2_b32 v144, v70, v74 offset0:8 offset1:24
	ds_write2_b32 v143, v71, v75 offset0:12 offset1:28
	ds_write2_b32 v142, v76, v80 offset0:64 offset1:80
	ds_write2_b32 v141, v77, v81 offset0:68 offset1:84
	ds_write2_b32 v140, v78, v82 offset0:72 offset1:88
	ds_write2_b32 v139, v79, v83 offset0:76 offset1:92
	ds_write2_b32 v147, v84, v88 offset0:128 offset1:144
	ds_write2_b32 v138, v85, v89 offset0:132 offset1:148
	ds_write2_b32 v136, v86, v90 offset0:136 offset1:152
	ds_write2_b32 v135, v87, v91 offset0:140 offset1:156
	ds_write2_b32 v146, v92, v96 offset0:192 offset1:208
	ds_write2_b32 v134, v93, v97 offset0:196 offset1:212
	ds_write2_b32 v133, v94, v98 offset0:200 offset1:216
	ds_write2_b32 v132, v95, v99 offset0:204 offset1:220
	ds_write2_b32 v219, v100, v104 offset0:128 offset1:144
	ds_write2_b32 v145, v101, v105 offset0:132 offset1:148
	ds_write2_b32 v144, v102, v106 offset0:136 offset1:152
	ds_write2_b32 v143, v103, v107 offset0:140 offset1:156
	ds_write2_b32 v142, v108, v112 offset0:192 offset1:208
	ds_write2_b32 v141, v109, v113 offset0:196 offset1:212
	ds_write2_b32 v140, v110, v114 offset0:200 offset1:216
	ds_write2_b32 v139, v111, v115 offset0:204 offset1:220
	ds_write2_b32 v138, v116, v120 offset1:16
	ds_write2_b32 v136, v117, v121 offset0:4 offset1:20
	ds_write2_b32 v135, v118, v122 offset0:8 offset1:24
	ds_write2_b32 v137, v119, v123 offset0:12 offset1:28
	ds_write2_b32 v134, v124, v128 offset0:64 offset1:80
	ds_write2_b32 v133, v125, v129 offset0:68 offset1:84
	ds_write2_b32 v132, v126, v130 offset0:72 offset1:88
	ds_write2_b32 v0, v127, v131 offset0:76 offset1:92
	s_waitcnt lgkmcnt(0)
	s_barrier
	v_add_u32_e32 v236, 0, v2
	v_ashrrev_i32_e32 v237, 31, v236
	v_lshlrev_b64 v[236:237], 10, v[236:237]
	v_lshl_add_u64 v[236:237], v[236:237], 0, v[198:199]
	v_lshlrev_b64 v[236:237], 1, v[236:237]
	v_lshl_add_u64 v[236:237], s[8:9], 0, v[236:237]
	global_load_dwordx4 v[148:151], v[236:237], off nt
	v_add_u32_e32 v236, 4, v2
	v_ashrrev_i32_e32 v237, 31, v236
	v_lshlrev_b64 v[236:237], 10, v[236:237]
	v_lshl_add_u64 v[236:237], v[236:237], 0, v[198:199]
	v_lshlrev_b64 v[236:237], 1, v[236:237]
	v_lshl_add_u64 v[236:237], s[8:9], 0, v[236:237]
	global_load_dwordx4 v[152:155], v[236:237], off nt
	v_add_u32_e32 v236, 8, v2
	v_ashrrev_i32_e32 v237, 31, v236
	v_lshlrev_b64 v[236:237], 10, v[236:237]
	v_lshl_add_u64 v[236:237], v[236:237], 0, v[198:199]
	v_lshlrev_b64 v[236:237], 1, v[236:237]
	v_lshl_add_u64 v[236:237], s[8:9], 0, v[236:237]
	global_load_dwordx4 v[156:159], v[236:237], off nt
	v_add_u32_e32 v236, 12, v2
	v_ashrrev_i32_e32 v237, 31, v236
	v_lshlrev_b64 v[236:237], 10, v[236:237]
	v_lshl_add_u64 v[236:237], v[236:237], 0, v[198:199]
	v_lshlrev_b64 v[236:237], 1, v[236:237]
	v_lshl_add_u64 v[236:237], s[8:9], 0, v[236:237]
	global_load_dwordx4 v[160:163], v[236:237], off nt
	v_add_u32_e32 v236, 16, v2
	v_ashrrev_i32_e32 v237, 31, v236
	v_lshlrev_b64 v[236:237], 10, v[236:237]
	v_lshl_add_u64 v[236:237], v[236:237], 0, v[198:199]
	v_lshlrev_b64 v[236:237], 1, v[236:237]
	v_lshl_add_u64 v[236:237], s[8:9], 0, v[236:237]
	global_load_dwordx4 v[164:167], v[236:237], off nt
	v_add_u32_e32 v236, 20, v2
	v_ashrrev_i32_e32 v237, 31, v236
	v_lshlrev_b64 v[236:237], 10, v[236:237]
	v_lshl_add_u64 v[236:237], v[236:237], 0, v[198:199]
	v_lshlrev_b64 v[236:237], 1, v[236:237]
	v_lshl_add_u64 v[236:237], s[8:9], 0, v[236:237]
	global_load_dwordx4 v[168:171], v[236:237], off nt
	v_add_u32_e32 v236, 24, v2
	v_ashrrev_i32_e32 v237, 31, v236
	v_lshlrev_b64 v[236:237], 10, v[236:237]
	v_lshl_add_u64 v[236:237], v[236:237], 0, v[198:199]
	v_lshlrev_b64 v[236:237], 1, v[236:237]
	v_lshl_add_u64 v[236:237], s[8:9], 0, v[236:237]
	global_load_dwordx4 v[172:175], v[236:237], off nt
	v_add_u32_e32 v236, 28, v2
	v_ashrrev_i32_e32 v237, 31, v236
	v_lshlrev_b64 v[236:237], 10, v[236:237]
	v_lshl_add_u64 v[236:237], v[236:237], 0, v[198:199]
	v_lshlrev_b64 v[236:237], 1, v[236:237]
	v_lshl_add_u64 v[236:237], s[8:9], 0, v[236:237]
	global_load_dwordx4 v[176:179], v[236:237], off nt
	ds_read_b128 v[180:183], v221 offset:0
	ds_read_b128 v[184:187], v221 offset:16
	v_add_u32_e32 v238, 0, v2
	v_ashrrev_i32_e32 v239, 31, v238
	v_lshlrev_b64 v[238:239], 10, v[238:239]
	v_lshl_add_u64 v[238:239], v[238:239], 0, v[198:199]
	v_lshlrev_b64 v[238:239], 1, v[238:239]
	v_lshl_add_u64 v[238:239], s[38:39], 0, v[238:239]
	s_waitcnt vmcnt(7)
	v_lshlrev_b32_e32 v200, 16, v148
	v_and_b32_e32 v201, 0xffff0000, v148
	v_lshlrev_b32_e32 v202, 16, v149
	v_and_b32_e32 v203, 0xffff0000, v149
	v_lshlrev_b32_e32 v204, 16, v150
	v_and_b32_e32 v205, 0xffff0000, v150
	v_lshlrev_b32_e32 v206, 16, v151
	v_and_b32_e32 v207, 0xffff0000, v151
	v_max_f32_e32 v200, v200, v200
	v_max_f32_e32 v201, v201, v201
	v_max_f32_e32 v202, v202, v202
	v_max_f32_e32 v203, v203, v203
	v_max_f32_e32 v204, v204, v204
	v_max_f32_e32 v205, v205, v205
	v_max_f32_e32 v206, v206, v206
	v_max_f32_e32 v207, v207, v207
	v_max_f32_e32 v200, 0xda24260, v200
	v_max_f32_e32 v201, 0xda24260, v201
	v_max_f32_e32 v202, 0xda24260, v202
	v_max_f32_e32 v203, 0xda24260, v203
	v_max_f32_e32 v204, 0xda24260, v204
	v_max_f32_e32 v205, 0xda24260, v205
	v_max_f32_e32 v206, 0xda24260, v206
	v_max_f32_e32 v207, 0xda24260, v207
	s_waitcnt lgkmcnt(0)
	v_pk_mul_f32 v[180:181], v[180:181], v[200:201]
	v_pk_mul_f32 v[182:183], v[182:183], v[202:203]
	v_pk_mul_f32 v[184:185], v[184:185], v[204:205]
	v_pk_mul_f32 v[186:187], v[186:187], v[206:207]
	v_cvt_pk_bf16_f32 v180, v180, v181
	v_cvt_pk_bf16_f32 v181, v182, v183
	v_cvt_pk_bf16_f32 v182, v184, v185
	v_cvt_pk_bf16_f32 v183, v186, v187
	global_store_dwordx4 v[238:239], v[180:183], off
	ds_read_b128 v[188:191], v221 offset:4160
	ds_read_b128 v[192:195], v221 offset:4176
	v_add_u32_e32 v240, 4, v2
	v_ashrrev_i32_e32 v241, 31, v240
	v_lshlrev_b64 v[240:241], 10, v[240:241]
	v_lshl_add_u64 v[240:241], v[240:241], 0, v[198:199]
	v_lshlrev_b64 v[240:241], 1, v[240:241]
	v_lshl_add_u64 v[240:241], s[38:39], 0, v[240:241]
	s_waitcnt vmcnt(7)
	v_lshlrev_b32_e32 v228, 16, v152
	v_and_b32_e32 v229, 0xffff0000, v152
	v_lshlrev_b32_e32 v230, 16, v153
	v_and_b32_e32 v231, 0xffff0000, v153
	v_lshlrev_b32_e32 v232, 16, v154
	v_and_b32_e32 v233, 0xffff0000, v154
	v_lshlrev_b32_e32 v234, 16, v155
	v_and_b32_e32 v235, 0xffff0000, v155
	v_max_f32_e32 v228, v228, v228
	v_max_f32_e32 v229, v229, v229
	v_max_f32_e32 v230, v230, v230
	v_max_f32_e32 v231, v231, v231
	v_max_f32_e32 v232, v232, v232
	v_max_f32_e32 v233, v233, v233
	v_max_f32_e32 v234, v234, v234
	v_max_f32_e32 v235, v235, v235
	v_max_f32_e32 v228, 0xda24260, v228
	v_max_f32_e32 v229, 0xda24260, v229
	v_max_f32_e32 v230, 0xda24260, v230
	v_max_f32_e32 v231, 0xda24260, v231
	v_max_f32_e32 v232, 0xda24260, v232
	v_max_f32_e32 v233, 0xda24260, v233
	v_max_f32_e32 v234, 0xda24260, v234
	v_max_f32_e32 v235, 0xda24260, v235
	s_waitcnt lgkmcnt(0)
	v_pk_mul_f32 v[188:189], v[188:189], v[228:229]
	v_pk_mul_f32 v[190:191], v[190:191], v[230:231]
	v_pk_mul_f32 v[192:193], v[192:193], v[232:233]
	v_pk_mul_f32 v[194:195], v[194:195], v[234:235]
	v_cvt_pk_bf16_f32 v188, v188, v189
	v_cvt_pk_bf16_f32 v189, v190, v191
	v_cvt_pk_bf16_f32 v190, v192, v193
	v_cvt_pk_bf16_f32 v191, v194, v195
	global_store_dwordx4 v[240:241], v[188:191], off
	ds_read_b128 v[180:183], v221 offset:8320
	ds_read_b128 v[184:187], v221 offset:8336
	v_add_u32_e32 v238, 8, v2
	v_ashrrev_i32_e32 v239, 31, v238
	v_lshlrev_b64 v[238:239], 10, v[238:239]
	v_lshl_add_u64 v[238:239], v[238:239], 0, v[198:199]
	v_lshlrev_b64 v[238:239], 1, v[238:239]
	v_lshl_add_u64 v[238:239], s[38:39], 0, v[238:239]
	s_waitcnt vmcnt(7)
	v_lshlrev_b32_e32 v200, 16, v156
	v_and_b32_e32 v201, 0xffff0000, v156
	v_lshlrev_b32_e32 v202, 16, v157
	v_and_b32_e32 v203, 0xffff0000, v157
	v_lshlrev_b32_e32 v204, 16, v158
	v_and_b32_e32 v205, 0xffff0000, v158
	v_lshlrev_b32_e32 v206, 16, v159
	v_and_b32_e32 v207, 0xffff0000, v159
	v_max_f32_e32 v200, v200, v200
	v_max_f32_e32 v201, v201, v201
	v_max_f32_e32 v202, v202, v202
	v_max_f32_e32 v203, v203, v203
	v_max_f32_e32 v204, v204, v204
	v_max_f32_e32 v205, v205, v205
	v_max_f32_e32 v206, v206, v206
	v_max_f32_e32 v207, v207, v207
	v_max_f32_e32 v200, 0xda24260, v200
	v_max_f32_e32 v201, 0xda24260, v201
	v_max_f32_e32 v202, 0xda24260, v202
	v_max_f32_e32 v203, 0xda24260, v203
	v_max_f32_e32 v204, 0xda24260, v204
	v_max_f32_e32 v205, 0xda24260, v205
	v_max_f32_e32 v206, 0xda24260, v206
	v_max_f32_e32 v207, 0xda24260, v207
	s_waitcnt lgkmcnt(0)
	v_pk_mul_f32 v[180:181], v[180:181], v[200:201]
	v_pk_mul_f32 v[182:183], v[182:183], v[202:203]
	v_pk_mul_f32 v[184:185], v[184:185], v[204:205]
	v_pk_mul_f32 v[186:187], v[186:187], v[206:207]
	v_cvt_pk_bf16_f32 v180, v180, v181
	v_cvt_pk_bf16_f32 v181, v182, v183
	v_cvt_pk_bf16_f32 v182, v184, v185
	v_cvt_pk_bf16_f32 v183, v186, v187
	global_store_dwordx4 v[238:239], v[180:183], off
	ds_read_b128 v[188:191], v221 offset:12480
	ds_read_b128 v[192:195], v221 offset:12496
	v_add_u32_e32 v240, 12, v2
	v_ashrrev_i32_e32 v241, 31, v240
	v_lshlrev_b64 v[240:241], 10, v[240:241]
	v_lshl_add_u64 v[240:241], v[240:241], 0, v[198:199]
	v_lshlrev_b64 v[240:241], 1, v[240:241]
	v_lshl_add_u64 v[240:241], s[38:39], 0, v[240:241]
	s_waitcnt vmcnt(7)
	v_lshlrev_b32_e32 v228, 16, v160
	v_and_b32_e32 v229, 0xffff0000, v160
	v_lshlrev_b32_e32 v230, 16, v161
	v_and_b32_e32 v231, 0xffff0000, v161
	v_lshlrev_b32_e32 v232, 16, v162
	v_and_b32_e32 v233, 0xffff0000, v162
	v_lshlrev_b32_e32 v234, 16, v163
	v_and_b32_e32 v235, 0xffff0000, v163
	v_max_f32_e32 v228, v228, v228
	v_max_f32_e32 v229, v229, v229
	v_max_f32_e32 v230, v230, v230
	v_max_f32_e32 v231, v231, v231
	v_max_f32_e32 v232, v232, v232
	v_max_f32_e32 v233, v233, v233
	v_max_f32_e32 v234, v234, v234
	v_max_f32_e32 v235, v235, v235
	v_max_f32_e32 v228, 0xda24260, v228
	v_max_f32_e32 v229, 0xda24260, v229
	v_max_f32_e32 v230, 0xda24260, v230
	v_max_f32_e32 v231, 0xda24260, v231
	v_max_f32_e32 v232, 0xda24260, v232
	v_max_f32_e32 v233, 0xda24260, v233
	v_max_f32_e32 v234, 0xda24260, v234
	v_max_f32_e32 v235, 0xda24260, v235
	s_waitcnt lgkmcnt(0)
	v_pk_mul_f32 v[188:189], v[188:189], v[228:229]
	v_pk_mul_f32 v[190:191], v[190:191], v[230:231]
	v_pk_mul_f32 v[192:193], v[192:193], v[232:233]
	v_pk_mul_f32 v[194:195], v[194:195], v[234:235]
	v_cvt_pk_bf16_f32 v188, v188, v189
	v_cvt_pk_bf16_f32 v189, v190, v191
	v_cvt_pk_bf16_f32 v190, v192, v193
	v_cvt_pk_bf16_f32 v191, v194, v195
	global_store_dwordx4 v[240:241], v[188:191], off
	ds_read_b128 v[180:183], v221 offset:16640
	ds_read_b128 v[184:187], v221 offset:16656
	v_add_u32_e32 v238, 16, v2
	v_ashrrev_i32_e32 v239, 31, v238
	v_lshlrev_b64 v[238:239], 10, v[238:239]
	v_lshl_add_u64 v[238:239], v[238:239], 0, v[198:199]
	v_lshlrev_b64 v[238:239], 1, v[238:239]
	v_lshl_add_u64 v[238:239], s[38:39], 0, v[238:239]
	s_waitcnt vmcnt(7)
	v_lshlrev_b32_e32 v200, 16, v164
	v_and_b32_e32 v201, 0xffff0000, v164
	v_lshlrev_b32_e32 v202, 16, v165
	v_and_b32_e32 v203, 0xffff0000, v165
	v_lshlrev_b32_e32 v204, 16, v166
	v_and_b32_e32 v205, 0xffff0000, v166
	v_lshlrev_b32_e32 v206, 16, v167
	v_and_b32_e32 v207, 0xffff0000, v167
	v_max_f32_e32 v200, v200, v200
	v_max_f32_e32 v201, v201, v201
	v_max_f32_e32 v202, v202, v202
	v_max_f32_e32 v203, v203, v203
	v_max_f32_e32 v204, v204, v204
	v_max_f32_e32 v205, v205, v205
	v_max_f32_e32 v206, v206, v206
	v_max_f32_e32 v207, v207, v207
	v_max_f32_e32 v200, 0xda24260, v200
	v_max_f32_e32 v201, 0xda24260, v201
	v_max_f32_e32 v202, 0xda24260, v202
	v_max_f32_e32 v203, 0xda24260, v203
	v_max_f32_e32 v204, 0xda24260, v204
	v_max_f32_e32 v205, 0xda24260, v205
	v_max_f32_e32 v206, 0xda24260, v206
	v_max_f32_e32 v207, 0xda24260, v207
	s_waitcnt lgkmcnt(0)
	v_pk_mul_f32 v[180:181], v[180:181], v[200:201]
	v_pk_mul_f32 v[182:183], v[182:183], v[202:203]
	v_pk_mul_f32 v[184:185], v[184:185], v[204:205]
	v_pk_mul_f32 v[186:187], v[186:187], v[206:207]
	v_cvt_pk_bf16_f32 v180, v180, v181
	v_cvt_pk_bf16_f32 v181, v182, v183
	v_cvt_pk_bf16_f32 v182, v184, v185
	v_cvt_pk_bf16_f32 v183, v186, v187
	global_store_dwordx4 v[238:239], v[180:183], off
	ds_read_b128 v[188:191], v221 offset:20800
	ds_read_b128 v[192:195], v221 offset:20816
	v_add_u32_e32 v240, 20, v2
	v_ashrrev_i32_e32 v241, 31, v240
	v_lshlrev_b64 v[240:241], 10, v[240:241]
	v_lshl_add_u64 v[240:241], v[240:241], 0, v[198:199]
	v_lshlrev_b64 v[240:241], 1, v[240:241]
	v_lshl_add_u64 v[240:241], s[38:39], 0, v[240:241]
	s_waitcnt vmcnt(7)
	v_lshlrev_b32_e32 v228, 16, v168
	v_and_b32_e32 v229, 0xffff0000, v168
	v_lshlrev_b32_e32 v230, 16, v169
	v_and_b32_e32 v231, 0xffff0000, v169
	v_lshlrev_b32_e32 v232, 16, v170
	v_and_b32_e32 v233, 0xffff0000, v170
	v_lshlrev_b32_e32 v234, 16, v171
	v_and_b32_e32 v235, 0xffff0000, v171
	v_max_f32_e32 v228, v228, v228
	v_max_f32_e32 v229, v229, v229
	v_max_f32_e32 v230, v230, v230
	v_max_f32_e32 v231, v231, v231
	v_max_f32_e32 v232, v232, v232
	v_max_f32_e32 v233, v233, v233
	v_max_f32_e32 v234, v234, v234
	v_max_f32_e32 v235, v235, v235
	v_max_f32_e32 v228, 0xda24260, v228
	v_max_f32_e32 v229, 0xda24260, v229
	v_max_f32_e32 v230, 0xda24260, v230
	v_max_f32_e32 v231, 0xda24260, v231
	v_max_f32_e32 v232, 0xda24260, v232
	v_max_f32_e32 v233, 0xda24260, v233
	v_max_f32_e32 v234, 0xda24260, v234
	v_max_f32_e32 v235, 0xda24260, v235
	s_waitcnt lgkmcnt(0)
	v_pk_mul_f32 v[188:189], v[188:189], v[228:229]
	v_pk_mul_f32 v[190:191], v[190:191], v[230:231]
	v_pk_mul_f32 v[192:193], v[192:193], v[232:233]
	v_pk_mul_f32 v[194:195], v[194:195], v[234:235]
	v_cvt_pk_bf16_f32 v188, v188, v189
	v_cvt_pk_bf16_f32 v189, v190, v191
	v_cvt_pk_bf16_f32 v190, v192, v193
	v_cvt_pk_bf16_f32 v191, v194, v195
	global_store_dwordx4 v[240:241], v[188:191], off
	ds_read_b128 v[180:183], v221 offset:24960
	ds_read_b128 v[184:187], v221 offset:24976
	v_add_u32_e32 v238, 24, v2
	v_ashrrev_i32_e32 v239, 31, v238
	v_lshlrev_b64 v[238:239], 10, v[238:239]
	v_lshl_add_u64 v[238:239], v[238:239], 0, v[198:199]
	v_lshlrev_b64 v[238:239], 1, v[238:239]
	v_lshl_add_u64 v[238:239], s[38:39], 0, v[238:239]
	s_waitcnt vmcnt(7)
	v_lshlrev_b32_e32 v200, 16, v172
	v_and_b32_e32 v201, 0xffff0000, v172
	v_lshlrev_b32_e32 v202, 16, v173
	v_and_b32_e32 v203, 0xffff0000, v173
	v_lshlrev_b32_e32 v204, 16, v174
	v_and_b32_e32 v205, 0xffff0000, v174
	v_lshlrev_b32_e32 v206, 16, v175
	v_and_b32_e32 v207, 0xffff0000, v175
	v_max_f32_e32 v200, v200, v200
	v_max_f32_e32 v201, v201, v201
	v_max_f32_e32 v202, v202, v202
	v_max_f32_e32 v203, v203, v203
	v_max_f32_e32 v204, v204, v204
	v_max_f32_e32 v205, v205, v205
	v_max_f32_e32 v206, v206, v206
	v_max_f32_e32 v207, v207, v207
	v_max_f32_e32 v200, 0xda24260, v200
	v_max_f32_e32 v201, 0xda24260, v201
	v_max_f32_e32 v202, 0xda24260, v202
	v_max_f32_e32 v203, 0xda24260, v203
	v_max_f32_e32 v204, 0xda24260, v204
	v_max_f32_e32 v205, 0xda24260, v205
	v_max_f32_e32 v206, 0xda24260, v206
	v_max_f32_e32 v207, 0xda24260, v207
	s_waitcnt lgkmcnt(0)
	v_pk_mul_f32 v[180:181], v[180:181], v[200:201]
	v_pk_mul_f32 v[182:183], v[182:183], v[202:203]
	v_pk_mul_f32 v[184:185], v[184:185], v[204:205]
	v_pk_mul_f32 v[186:187], v[186:187], v[206:207]
	v_cvt_pk_bf16_f32 v180, v180, v181
	v_cvt_pk_bf16_f32 v181, v182, v183
	v_cvt_pk_bf16_f32 v182, v184, v185
	v_cvt_pk_bf16_f32 v183, v186, v187
	global_store_dwordx4 v[238:239], v[180:183], off
	ds_read_b128 v[188:191], v221 offset:29120
	ds_read_b128 v[192:195], v221 offset:29136
	v_add_u32_e32 v240, 28, v2
	v_ashrrev_i32_e32 v241, 31, v240
	v_lshlrev_b64 v[240:241], 10, v[240:241]
	v_lshl_add_u64 v[240:241], v[240:241], 0, v[198:199]
	v_lshlrev_b64 v[240:241], 1, v[240:241]
	v_lshl_add_u64 v[240:241], s[38:39], 0, v[240:241]
	s_waitcnt vmcnt(7)
	v_lshlrev_b32_e32 v228, 16, v176
	v_and_b32_e32 v229, 0xffff0000, v176
	v_lshlrev_b32_e32 v230, 16, v177
	v_and_b32_e32 v231, 0xffff0000, v177
	v_lshlrev_b32_e32 v232, 16, v178
	v_and_b32_e32 v233, 0xffff0000, v178
	v_lshlrev_b32_e32 v234, 16, v179
	v_and_b32_e32 v235, 0xffff0000, v179
	v_max_f32_e32 v228, v228, v228
	v_max_f32_e32 v229, v229, v229
	v_max_f32_e32 v230, v230, v230
	v_max_f32_e32 v231, v231, v231
	v_max_f32_e32 v232, v232, v232
	v_max_f32_e32 v233, v233, v233
	v_max_f32_e32 v234, v234, v234
	v_max_f32_e32 v235, v235, v235
	v_max_f32_e32 v228, 0xda24260, v228
	v_max_f32_e32 v229, 0xda24260, v229
	v_max_f32_e32 v230, 0xda24260, v230
	v_max_f32_e32 v231, 0xda24260, v231
	v_max_f32_e32 v232, 0xda24260, v232
	v_max_f32_e32 v233, 0xda24260, v233
	v_max_f32_e32 v234, 0xda24260, v234
	v_max_f32_e32 v235, 0xda24260, v235
	s_waitcnt lgkmcnt(0)
	v_pk_mul_f32 v[188:189], v[188:189], v[228:229]
	v_pk_mul_f32 v[190:191], v[190:191], v[230:231]
	v_pk_mul_f32 v[192:193], v[192:193], v[232:233]
	v_pk_mul_f32 v[194:195], v[194:195], v[234:235]
	v_cvt_pk_bf16_f32 v188, v188, v189
	v_cvt_pk_bf16_f32 v189, v190, v191
	v_cvt_pk_bf16_f32 v190, v192, v193
	v_cvt_pk_bf16_f32 v191, v194, v195
	global_store_dwordx4 v[240:241], v[188:191], off
	s_andn2_b64 vcc, exec, s[24:25]
	s_cbranch_vccnz .LBB0_558
	s_waitcnt lgkmcnt(0)
	s_mov_b32 s2, 0
	v_mov_b32_e32 v2, v226
	s_barrier
	ds_write2_b32 v219, v8, v4 offset1:16
	ds_write2_b32 v145, v9, v5 offset0:4 offset1:20
	ds_write2_b32 v144, v10, v6 offset0:8 offset1:24
	ds_write2_b32 v143, v11, v7 offset0:12 offset1:28
	ds_write2_b32 v142, v16, v12 offset0:64 offset1:80
	ds_write2_b32 v141, v17, v13 offset0:68 offset1:84
	ds_write2_b32 v140, v18, v14 offset0:72 offset1:88
	ds_write2_b32 v139, v19, v15 offset0:76 offset1:92
	ds_write2_b32 v147, v24, v20 offset0:128 offset1:144
	ds_write2_b32 v138, v25, v21 offset0:132 offset1:148
	ds_write2_b32 v136, v26, v22 offset0:136 offset1:152
	ds_write2_b32 v135, v27, v23 offset0:140 offset1:156
	ds_write2_b32 v146, v32, v28 offset0:192 offset1:208
	ds_write2_b32 v134, v33, v29 offset0:196 offset1:212
	ds_write2_b32 v133, v34, v30 offset0:200 offset1:216
	ds_write2_b32 v132, v35, v31 offset0:204 offset1:220
	ds_write2_b32 v219, v40, v36 offset0:128 offset1:144
	ds_write2_b32 v145, v41, v37 offset0:132 offset1:148
	ds_write2_b32 v144, v42, v38 offset0:136 offset1:152
	ds_write2_b32 v143, v43, v39 offset0:140 offset1:156
	ds_write2_b32 v142, v48, v44 offset0:192 offset1:208
	ds_write2_b32 v141, v49, v45 offset0:196 offset1:212
	ds_write2_b32 v140, v50, v46 offset0:200 offset1:216
	ds_write2_b32 v139, v51, v47 offset0:204 offset1:220
	ds_write2_b32 v138, v56, v52 offset1:16
	ds_write2_b32 v136, v57, v53 offset0:4 offset1:20
	ds_write2_b32 v135, v58, v54 offset0:8 offset1:24
	ds_write2_b32 v137, v59, v55 offset0:12 offset1:28
	ds_write2_b32 v134, v64, v60 offset0:64 offset1:80
	ds_write2_b32 v133, v65, v61 offset0:68 offset1:84
	ds_write2_b32 v132, v66, v62 offset0:72 offset1:88
	ds_write2_b32 v0, v67, v63 offset0:76 offset1:92
	s_waitcnt lgkmcnt(0)
	s_barrier
	v_add_u32_e32 v236, -4, v2
	v_ashrrev_i32_e32 v237, 31, v236
	v_lshlrev_b64 v[236:237], 10, v[236:237]
	v_lshl_add_u64 v[236:237], v[236:237], 0, v[198:199]
	v_lshlrev_b64 v[236:237], 1, v[236:237]
	v_lshl_add_u64 v[236:237], s[8:9], 0, v[236:237]
	global_load_dwordx4 v[148:151], v[236:237], off nt
	v_add_u32_e32 v236, 0, v2
	v_ashrrev_i32_e32 v237, 31, v236
	v_lshlrev_b64 v[236:237], 10, v[236:237]
	v_lshl_add_u64 v[236:237], v[236:237], 0, v[198:199]
	v_lshlrev_b64 v[236:237], 1, v[236:237]
	v_lshl_add_u64 v[236:237], s[8:9], 0, v[236:237]
	global_load_dwordx4 v[152:155], v[236:237], off nt
	v_add_u32_e32 v236, 4, v2
	v_ashrrev_i32_e32 v237, 31, v236
	v_lshlrev_b64 v[236:237], 10, v[236:237]
	v_lshl_add_u64 v[236:237], v[236:237], 0, v[198:199]
	v_lshlrev_b64 v[236:237], 1, v[236:237]
	v_lshl_add_u64 v[236:237], s[8:9], 0, v[236:237]
	global_load_dwordx4 v[156:159], v[236:237], off nt
	v_add_u32_e32 v236, 8, v2
	v_ashrrev_i32_e32 v237, 31, v236
	v_lshlrev_b64 v[236:237], 10, v[236:237]
	v_lshl_add_u64 v[236:237], v[236:237], 0, v[198:199]
	v_lshlrev_b64 v[236:237], 1, v[236:237]
	v_lshl_add_u64 v[236:237], s[8:9], 0, v[236:237]
	global_load_dwordx4 v[160:163], v[236:237], off nt
	v_add_u32_e32 v236, 12, v2
	v_ashrrev_i32_e32 v237, 31, v236
	v_lshlrev_b64 v[236:237], 10, v[236:237]
	v_lshl_add_u64 v[236:237], v[236:237], 0, v[198:199]
	v_lshlrev_b64 v[236:237], 1, v[236:237]
	v_lshl_add_u64 v[236:237], s[8:9], 0, v[236:237]
	global_load_dwordx4 v[164:167], v[236:237], off nt
	v_add_u32_e32 v236, 16, v2
	v_ashrrev_i32_e32 v237, 31, v236
	v_lshlrev_b64 v[236:237], 10, v[236:237]
	v_lshl_add_u64 v[236:237], v[236:237], 0, v[198:199]
	v_lshlrev_b64 v[236:237], 1, v[236:237]
	v_lshl_add_u64 v[236:237], s[8:9], 0, v[236:237]
	global_load_dwordx4 v[168:171], v[236:237], off nt
	v_add_u32_e32 v236, 20, v2
	v_ashrrev_i32_e32 v237, 31, v236
	v_lshlrev_b64 v[236:237], 10, v[236:237]
	v_lshl_add_u64 v[236:237], v[236:237], 0, v[198:199]
	v_lshlrev_b64 v[236:237], 1, v[236:237]
	v_lshl_add_u64 v[236:237], s[8:9], 0, v[236:237]
	global_load_dwordx4 v[172:175], v[236:237], off nt
	v_add_u32_e32 v236, 24, v2
	v_ashrrev_i32_e32 v237, 31, v236
	v_lshlrev_b64 v[236:237], 10, v[236:237]
	v_lshl_add_u64 v[236:237], v[236:237], 0, v[198:199]
	v_lshlrev_b64 v[236:237], 1, v[236:237]
	v_lshl_add_u64 v[236:237], s[8:9], 0, v[236:237]
	global_load_dwordx4 v[176:179], v[236:237], off nt
	ds_read_b128 v[180:183], v221 offset:0
	ds_read_b128 v[184:187], v221 offset:16
	v_add_u32_e32 v238, -4, v2
	v_ashrrev_i32_e32 v239, 31, v238
	v_lshlrev_b64 v[238:239], 10, v[238:239]
	v_lshl_add_u64 v[238:239], v[238:239], 0, v[198:199]
	v_lshlrev_b64 v[238:239], 1, v[238:239]
	v_lshl_add_u64 v[238:239], s[38:39], 0, v[238:239]
	s_waitcnt vmcnt(7)
	v_lshlrev_b32_e32 v200, 16, v148
	v_and_b32_e32 v201, 0xffff0000, v148
	v_lshlrev_b32_e32 v202, 16, v149
	v_and_b32_e32 v203, 0xffff0000, v149
	v_lshlrev_b32_e32 v204, 16, v150
	v_and_b32_e32 v205, 0xffff0000, v150
	v_lshlrev_b32_e32 v206, 16, v151
	v_and_b32_e32 v207, 0xffff0000, v151
	v_max_f32_e32 v200, v200, v200
	v_max_f32_e32 v201, v201, v201
	v_max_f32_e32 v202, v202, v202
	v_max_f32_e32 v203, v203, v203
	v_max_f32_e32 v204, v204, v204
	v_max_f32_e32 v205, v205, v205
	v_max_f32_e32 v206, v206, v206
	v_max_f32_e32 v207, v207, v207
	v_max_f32_e32 v200, 0xda24260, v200
	v_max_f32_e32 v201, 0xda24260, v201
	v_max_f32_e32 v202, 0xda24260, v202
	v_max_f32_e32 v203, 0xda24260, v203
	v_max_f32_e32 v204, 0xda24260, v204
	v_max_f32_e32 v205, 0xda24260, v205
	v_max_f32_e32 v206, 0xda24260, v206
	v_max_f32_e32 v207, 0xda24260, v207
	s_waitcnt lgkmcnt(0)
	v_pk_mul_f32 v[180:181], v[180:181], v[200:201]
	v_pk_mul_f32 v[182:183], v[182:183], v[202:203]
	v_pk_mul_f32 v[184:185], v[184:185], v[204:205]
	v_pk_mul_f32 v[186:187], v[186:187], v[206:207]
	v_cvt_pk_bf16_f32 v180, v180, v181
	v_cvt_pk_bf16_f32 v181, v182, v183
	v_cvt_pk_bf16_f32 v182, v184, v185
	v_cvt_pk_bf16_f32 v183, v186, v187
	global_store_dwordx4 v[238:239], v[180:183], off
	ds_read_b128 v[188:191], v221 offset:4160
	ds_read_b128 v[192:195], v221 offset:4176
	v_add_u32_e32 v240, 0, v2
	v_ashrrev_i32_e32 v241, 31, v240
	v_lshlrev_b64 v[240:241], 10, v[240:241]
	v_lshl_add_u64 v[240:241], v[240:241], 0, v[198:199]
	v_lshlrev_b64 v[240:241], 1, v[240:241]
	v_lshl_add_u64 v[240:241], s[38:39], 0, v[240:241]
	s_waitcnt vmcnt(7)
	v_lshlrev_b32_e32 v228, 16, v152
	v_and_b32_e32 v229, 0xffff0000, v152
	v_lshlrev_b32_e32 v230, 16, v153
	v_and_b32_e32 v231, 0xffff0000, v153
	v_lshlrev_b32_e32 v232, 16, v154
	v_and_b32_e32 v233, 0xffff0000, v154
	v_lshlrev_b32_e32 v234, 16, v155
	v_and_b32_e32 v235, 0xffff0000, v155
	v_max_f32_e32 v228, v228, v228
	v_max_f32_e32 v229, v229, v229
	v_max_f32_e32 v230, v230, v230
	v_max_f32_e32 v231, v231, v231
	v_max_f32_e32 v232, v232, v232
	v_max_f32_e32 v233, v233, v233
	v_max_f32_e32 v234, v234, v234
	v_max_f32_e32 v235, v235, v235
	v_max_f32_e32 v228, 0xda24260, v228
	v_max_f32_e32 v229, 0xda24260, v229
	v_max_f32_e32 v230, 0xda24260, v230
	v_max_f32_e32 v231, 0xda24260, v231
	v_max_f32_e32 v232, 0xda24260, v232
	v_max_f32_e32 v233, 0xda24260, v233
	v_max_f32_e32 v234, 0xda24260, v234
	v_max_f32_e32 v235, 0xda24260, v235
	s_waitcnt lgkmcnt(0)
	v_pk_mul_f32 v[188:189], v[188:189], v[228:229]
	v_pk_mul_f32 v[190:191], v[190:191], v[230:231]
	v_pk_mul_f32 v[192:193], v[192:193], v[232:233]
	v_pk_mul_f32 v[194:195], v[194:195], v[234:235]
	v_cvt_pk_bf16_f32 v188, v188, v189
	v_cvt_pk_bf16_f32 v189, v190, v191
	v_cvt_pk_bf16_f32 v190, v192, v193
	v_cvt_pk_bf16_f32 v191, v194, v195
	global_store_dwordx4 v[240:241], v[188:191], off
	ds_read_b128 v[180:183], v221 offset:8320
	ds_read_b128 v[184:187], v221 offset:8336
	v_add_u32_e32 v238, 4, v2
	v_ashrrev_i32_e32 v239, 31, v238
	v_lshlrev_b64 v[238:239], 10, v[238:239]
	v_lshl_add_u64 v[238:239], v[238:239], 0, v[198:199]
	v_lshlrev_b64 v[238:239], 1, v[238:239]
	v_lshl_add_u64 v[238:239], s[38:39], 0, v[238:239]
	s_waitcnt vmcnt(7)
	v_lshlrev_b32_e32 v200, 16, v156
	v_and_b32_e32 v201, 0xffff0000, v156
	v_lshlrev_b32_e32 v202, 16, v157
	v_and_b32_e32 v203, 0xffff0000, v157
	v_lshlrev_b32_e32 v204, 16, v158
	v_and_b32_e32 v205, 0xffff0000, v158
	v_lshlrev_b32_e32 v206, 16, v159
	v_and_b32_e32 v207, 0xffff0000, v159
	v_max_f32_e32 v200, v200, v200
	v_max_f32_e32 v201, v201, v201
	v_max_f32_e32 v202, v202, v202
	v_max_f32_e32 v203, v203, v203
	v_max_f32_e32 v204, v204, v204
	v_max_f32_e32 v205, v205, v205
	v_max_f32_e32 v206, v206, v206
	v_max_f32_e32 v207, v207, v207
	v_max_f32_e32 v200, 0xda24260, v200
	v_max_f32_e32 v201, 0xda24260, v201
	v_max_f32_e32 v202, 0xda24260, v202
	v_max_f32_e32 v203, 0xda24260, v203
	v_max_f32_e32 v204, 0xda24260, v204
	v_max_f32_e32 v205, 0xda24260, v205
	v_max_f32_e32 v206, 0xda24260, v206
	v_max_f32_e32 v207, 0xda24260, v207
	s_waitcnt lgkmcnt(0)
	v_pk_mul_f32 v[180:181], v[180:181], v[200:201]
	v_pk_mul_f32 v[182:183], v[182:183], v[202:203]
	v_pk_mul_f32 v[184:185], v[184:185], v[204:205]
	v_pk_mul_f32 v[186:187], v[186:187], v[206:207]
	v_cvt_pk_bf16_f32 v180, v180, v181
	v_cvt_pk_bf16_f32 v181, v182, v183
	v_cvt_pk_bf16_f32 v182, v184, v185
	v_cvt_pk_bf16_f32 v183, v186, v187
	global_store_dwordx4 v[238:239], v[180:183], off
	ds_read_b128 v[188:191], v221 offset:12480
	ds_read_b128 v[192:195], v221 offset:12496
	v_add_u32_e32 v240, 8, v2
	v_ashrrev_i32_e32 v241, 31, v240
	v_lshlrev_b64 v[240:241], 10, v[240:241]
	v_lshl_add_u64 v[240:241], v[240:241], 0, v[198:199]
	v_lshlrev_b64 v[240:241], 1, v[240:241]
	v_lshl_add_u64 v[240:241], s[38:39], 0, v[240:241]
	s_waitcnt vmcnt(7)
	v_lshlrev_b32_e32 v228, 16, v160
	v_and_b32_e32 v229, 0xffff0000, v160
	v_lshlrev_b32_e32 v230, 16, v161
	v_and_b32_e32 v231, 0xffff0000, v161
	v_lshlrev_b32_e32 v232, 16, v162
	v_and_b32_e32 v233, 0xffff0000, v162
	v_lshlrev_b32_e32 v234, 16, v163
	v_and_b32_e32 v235, 0xffff0000, v163
	v_max_f32_e32 v228, v228, v228
	v_max_f32_e32 v229, v229, v229
	v_max_f32_e32 v230, v230, v230
	v_max_f32_e32 v231, v231, v231
	v_max_f32_e32 v232, v232, v232
	v_max_f32_e32 v233, v233, v233
	v_max_f32_e32 v234, v234, v234
	v_max_f32_e32 v235, v235, v235
	v_max_f32_e32 v228, 0xda24260, v228
	v_max_f32_e32 v229, 0xda24260, v229
	v_max_f32_e32 v230, 0xda24260, v230
	v_max_f32_e32 v231, 0xda24260, v231
	v_max_f32_e32 v232, 0xda24260, v232
	v_max_f32_e32 v233, 0xda24260, v233
	v_max_f32_e32 v234, 0xda24260, v234
	v_max_f32_e32 v235, 0xda24260, v235
	s_waitcnt lgkmcnt(0)
	v_pk_mul_f32 v[188:189], v[188:189], v[228:229]
	v_pk_mul_f32 v[190:191], v[190:191], v[230:231]
	v_pk_mul_f32 v[192:193], v[192:193], v[232:233]
	v_pk_mul_f32 v[194:195], v[194:195], v[234:235]
	v_cvt_pk_bf16_f32 v188, v188, v189
	v_cvt_pk_bf16_f32 v189, v190, v191
	v_cvt_pk_bf16_f32 v190, v192, v193
	v_cvt_pk_bf16_f32 v191, v194, v195
	global_store_dwordx4 v[240:241], v[188:191], off
	ds_read_b128 v[180:183], v221 offset:16640
	ds_read_b128 v[184:187], v221 offset:16656
	v_add_u32_e32 v238, 12, v2
	v_ashrrev_i32_e32 v239, 31, v238
	v_lshlrev_b64 v[238:239], 10, v[238:239]
	v_lshl_add_u64 v[238:239], v[238:239], 0, v[198:199]
	v_lshlrev_b64 v[238:239], 1, v[238:239]
	v_lshl_add_u64 v[238:239], s[38:39], 0, v[238:239]
	s_waitcnt vmcnt(7)
	v_lshlrev_b32_e32 v200, 16, v164
	v_and_b32_e32 v201, 0xffff0000, v164
	v_lshlrev_b32_e32 v202, 16, v165
	v_and_b32_e32 v203, 0xffff0000, v165
	v_lshlrev_b32_e32 v204, 16, v166
	v_and_b32_e32 v205, 0xffff0000, v166
	v_lshlrev_b32_e32 v206, 16, v167
	v_and_b32_e32 v207, 0xffff0000, v167
	v_max_f32_e32 v200, v200, v200
	v_max_f32_e32 v201, v201, v201
	v_max_f32_e32 v202, v202, v202
	v_max_f32_e32 v203, v203, v203
	v_max_f32_e32 v204, v204, v204
	v_max_f32_e32 v205, v205, v205
	v_max_f32_e32 v206, v206, v206
	v_max_f32_e32 v207, v207, v207
	v_max_f32_e32 v200, 0xda24260, v200
	v_max_f32_e32 v201, 0xda24260, v201
	v_max_f32_e32 v202, 0xda24260, v202
	v_max_f32_e32 v203, 0xda24260, v203
	v_max_f32_e32 v204, 0xda24260, v204
	v_max_f32_e32 v205, 0xda24260, v205
	v_max_f32_e32 v206, 0xda24260, v206
	v_max_f32_e32 v207, 0xda24260, v207
	s_waitcnt lgkmcnt(0)
	v_pk_mul_f32 v[180:181], v[180:181], v[200:201]
	v_pk_mul_f32 v[182:183], v[182:183], v[202:203]
	v_pk_mul_f32 v[184:185], v[184:185], v[204:205]
	v_pk_mul_f32 v[186:187], v[186:187], v[206:207]
	v_cvt_pk_bf16_f32 v180, v180, v181
	v_cvt_pk_bf16_f32 v181, v182, v183
	v_cvt_pk_bf16_f32 v182, v184, v185
	v_cvt_pk_bf16_f32 v183, v186, v187
	global_store_dwordx4 v[238:239], v[180:183], off
	ds_read_b128 v[188:191], v221 offset:20800
	ds_read_b128 v[192:195], v221 offset:20816
	v_add_u32_e32 v240, 16, v2
	v_ashrrev_i32_e32 v241, 31, v240
	v_lshlrev_b64 v[240:241], 10, v[240:241]
	v_lshl_add_u64 v[240:241], v[240:241], 0, v[198:199]
	v_lshlrev_b64 v[240:241], 1, v[240:241]
	v_lshl_add_u64 v[240:241], s[38:39], 0, v[240:241]
	s_waitcnt vmcnt(7)
	v_lshlrev_b32_e32 v228, 16, v168
	v_and_b32_e32 v229, 0xffff0000, v168
	v_lshlrev_b32_e32 v230, 16, v169
	v_and_b32_e32 v231, 0xffff0000, v169
	v_lshlrev_b32_e32 v232, 16, v170
	v_and_b32_e32 v233, 0xffff0000, v170
	v_lshlrev_b32_e32 v234, 16, v171
	v_and_b32_e32 v235, 0xffff0000, v171
	v_max_f32_e32 v228, v228, v228
	v_max_f32_e32 v229, v229, v229
	v_max_f32_e32 v230, v230, v230
	v_max_f32_e32 v231, v231, v231
	v_max_f32_e32 v232, v232, v232
	v_max_f32_e32 v233, v233, v233
	v_max_f32_e32 v234, v234, v234
	v_max_f32_e32 v235, v235, v235
	v_max_f32_e32 v228, 0xda24260, v228
	v_max_f32_e32 v229, 0xda24260, v229
	v_max_f32_e32 v230, 0xda24260, v230
	v_max_f32_e32 v231, 0xda24260, v231
	v_max_f32_e32 v232, 0xda24260, v232
	v_max_f32_e32 v233, 0xda24260, v233
	v_max_f32_e32 v234, 0xda24260, v234
	v_max_f32_e32 v235, 0xda24260, v235
	s_waitcnt lgkmcnt(0)
	v_pk_mul_f32 v[188:189], v[188:189], v[228:229]
	v_pk_mul_f32 v[190:191], v[190:191], v[230:231]
	v_pk_mul_f32 v[192:193], v[192:193], v[232:233]
	v_pk_mul_f32 v[194:195], v[194:195], v[234:235]
	v_cvt_pk_bf16_f32 v188, v188, v189
	v_cvt_pk_bf16_f32 v189, v190, v191
	v_cvt_pk_bf16_f32 v190, v192, v193
	v_cvt_pk_bf16_f32 v191, v194, v195
	global_store_dwordx4 v[240:241], v[188:191], off
	ds_read_b128 v[180:183], v221 offset:24960
	ds_read_b128 v[184:187], v221 offset:24976
	v_add_u32_e32 v238, 20, v2
	v_ashrrev_i32_e32 v239, 31, v238
	v_lshlrev_b64 v[238:239], 10, v[238:239]
	v_lshl_add_u64 v[238:239], v[238:239], 0, v[198:199]
	v_lshlrev_b64 v[238:239], 1, v[238:239]
	v_lshl_add_u64 v[238:239], s[38:39], 0, v[238:239]
	s_waitcnt vmcnt(7)
	v_lshlrev_b32_e32 v200, 16, v172
	v_and_b32_e32 v201, 0xffff0000, v172
	v_lshlrev_b32_e32 v202, 16, v173
	v_and_b32_e32 v203, 0xffff0000, v173
	v_lshlrev_b32_e32 v204, 16, v174
	v_and_b32_e32 v205, 0xffff0000, v174
	v_lshlrev_b32_e32 v206, 16, v175
	v_and_b32_e32 v207, 0xffff0000, v175
	v_max_f32_e32 v200, v200, v200
	v_max_f32_e32 v201, v201, v201
	v_max_f32_e32 v202, v202, v202
	v_max_f32_e32 v203, v203, v203
	v_max_f32_e32 v204, v204, v204
	v_max_f32_e32 v205, v205, v205
	v_max_f32_e32 v206, v206, v206
	v_max_f32_e32 v207, v207, v207
	v_max_f32_e32 v200, 0xda24260, v200
	v_max_f32_e32 v201, 0xda24260, v201
	v_max_f32_e32 v202, 0xda24260, v202
	v_max_f32_e32 v203, 0xda24260, v203
	v_max_f32_e32 v204, 0xda24260, v204
	v_max_f32_e32 v205, 0xda24260, v205
	v_max_f32_e32 v206, 0xda24260, v206
	v_max_f32_e32 v207, 0xda24260, v207
	s_waitcnt lgkmcnt(0)
	v_pk_mul_f32 v[180:181], v[180:181], v[200:201]
	v_pk_mul_f32 v[182:183], v[182:183], v[202:203]
	v_pk_mul_f32 v[184:185], v[184:185], v[204:205]
	v_pk_mul_f32 v[186:187], v[186:187], v[206:207]
	v_cvt_pk_bf16_f32 v180, v180, v181
	v_cvt_pk_bf16_f32 v181, v182, v183
	v_cvt_pk_bf16_f32 v182, v184, v185
	v_cvt_pk_bf16_f32 v183, v186, v187
	global_store_dwordx4 v[238:239], v[180:183], off
	ds_read_b128 v[188:191], v221 offset:29120
	ds_read_b128 v[192:195], v221 offset:29136
	v_add_u32_e32 v240, 24, v2
	v_ashrrev_i32_e32 v241, 31, v240
	v_lshlrev_b64 v[240:241], 10, v[240:241]
	v_lshl_add_u64 v[240:241], v[240:241], 0, v[198:199]
	v_lshlrev_b64 v[240:241], 1, v[240:241]
	v_lshl_add_u64 v[240:241], s[38:39], 0, v[240:241]
	s_waitcnt vmcnt(7)
	v_lshlrev_b32_e32 v228, 16, v176
	v_and_b32_e32 v229, 0xffff0000, v176
	v_lshlrev_b32_e32 v230, 16, v177
	v_and_b32_e32 v231, 0xffff0000, v177
	v_lshlrev_b32_e32 v232, 16, v178
	v_and_b32_e32 v233, 0xffff0000, v178
	v_lshlrev_b32_e32 v234, 16, v179
	v_and_b32_e32 v235, 0xffff0000, v179
	v_max_f32_e32 v228, v228, v228
	v_max_f32_e32 v229, v229, v229
	v_max_f32_e32 v230, v230, v230
	v_max_f32_e32 v231, v231, v231
	v_max_f32_e32 v232, v232, v232
	v_max_f32_e32 v233, v233, v233
	v_max_f32_e32 v234, v234, v234
	v_max_f32_e32 v235, v235, v235
	v_max_f32_e32 v228, 0xda24260, v228
	v_max_f32_e32 v229, 0xda24260, v229
	v_max_f32_e32 v230, 0xda24260, v230
	v_max_f32_e32 v231, 0xda24260, v231
	v_max_f32_e32 v232, 0xda24260, v232
	v_max_f32_e32 v233, 0xda24260, v233
	v_max_f32_e32 v234, 0xda24260, v234
	v_max_f32_e32 v235, 0xda24260, v235
	s_waitcnt lgkmcnt(0)
	v_pk_mul_f32 v[188:189], v[188:189], v[228:229]
	v_pk_mul_f32 v[190:191], v[190:191], v[230:231]
	v_pk_mul_f32 v[192:193], v[192:193], v[232:233]
	v_pk_mul_f32 v[194:195], v[194:195], v[234:235]
	v_cvt_pk_bf16_f32 v188, v188, v189
	v_cvt_pk_bf16_f32 v189, v190, v191
	v_cvt_pk_bf16_f32 v190, v192, v193
	v_cvt_pk_bf16_f32 v191, v194, v195
	global_store_dwordx4 v[240:241], v[188:191], off

.LBB0_561:
	v_ashrrev_i32_e32 v3, 31, v2
	v_add_u32_e32 v84, 4, v2
	v_lshlrev_b64 v[86:87], 10, v[2:3]
	v_ashrrev_i32_e32 v85, 31, v84
	v_lshl_add_u64 v[86:87], v[86:87], 0, v[198:199]
	v_lshlrev_b64 v[84:85], 10, v[84:85]
	v_lshlrev_b64 v[86:87], 1, v[86:87]
	v_lshl_add_u64 v[84:85], v[84:85], 0, v[198:199]
	v_add_u32_e32 v116, s2, v221
	v_lshl_add_u64 v[88:89], s[6:7], 0, v[86:87]
	v_lshl_add_u64 v[86:87], s[8:9], 0, v[86:87]
	v_lshlrev_b64 v[92:93], 1, v[84:85]
	ds_read_b128 v[68:71], v116
	ds_read_b128 v[72:75], v116 offset:16
	ds_read_b128 v[76:79], v116 offset:4160
	ds_read_b128 v[80:83], v116 offset:4176
	global_load_dwordx4 v[84:87], v[86:87], off
	s_nop 0
	global_load_dwordx4 v[88:91], v[88:89], off nt
	v_lshl_add_u64 v[96:97], s[6:7], 0, v[92:93]
	v_lshl_add_u64 v[92:93], s[8:9], 0, v[92:93]
	global_load_dwordx4 v[92:95], v[92:93], off
	s_nop 0
	global_load_dwordx4 v[96:99], v[96:97], off nt
	s_addk_i32 s2, 0x2080
	v_add_u32_e32 v2, 8, v2
	s_cmpk_lg_u32 s2, 0x8200
	s_waitcnt vmcnt(3)
	v_lshlrev_b32_e32 v3, 16, v84
	v_and_b32_e32 v100, 0xffff0000, v84
	v_lshlrev_b32_e32 v101, 16, v85
	v_and_b32_e32 v102, 0xffff0000, v85
	v_lshlrev_b32_e32 v103, 16, v86
	v_and_b32_e32 v104, 0xffff0000, v86
	v_lshlrev_b32_e32 v105, 16, v87
	v_and_b32_e32 v106, 0xffff0000, v87
	v_max_f32_e32 v3, v3, v3
	v_max_f32_e32 v100, v100, v100
	v_max_f32_e32 v101, v101, v101
	v_max_f32_e32 v102, v102, v102
	s_waitcnt vmcnt(1)
	v_lshlrev_b32_e32 v107, 16, v92
	v_and_b32_e32 v108, 0xffff0000, v92
	v_lshlrev_b32_e32 v109, 16, v93
	v_and_b32_e32 v110, 0xffff0000, v93
	v_max_f32_e32 v103, v103, v103
	v_max_f32_e32 v104, v104, v104
	v_max_f32_e32 v105, v105, v105
	v_max_f32_e32 v106, v106, v106
	v_lshlrev_b32_e32 v111, 16, v94
	v_and_b32_e32 v112, 0xffff0000, v94
	v_lshlrev_b32_e32 v113, 16, v95
	v_and_b32_e32 v114, 0xffff0000, v95
	v_max_f32_e32 v3, 0xda24260, v3
	v_max_f32_e32 v115, 0xda24260, v100
	v_max_f32_e32 v117, 0xda24260, v101
	v_max_f32_e32 v118, 0xda24260, v102
	v_max_f32_e32 v123, v107, v107
	v_max_f32_e32 v108, v108, v108
	v_max_f32_e32 v109, v109, v109
	v_max_f32_e32 v110, v110, v110
	v_max_f32_e32 v119, 0xda24260, v103
	v_max_f32_e32 v120, 0xda24260, v104
	v_max_f32_e32 v121, 0xda24260, v105
	v_max_f32_e32 v122, 0xda24260, v106
	v_max_f32_e32 v111, v111, v111
	v_max_f32_e32 v112, v112, v112
	v_max_f32_e32 v113, v113, v113
	v_max_f32_e32 v114, v114, v114
	v_rcp_f32_e32 v100, v3
	v_rcp_f32_e32 v101, v115
	v_rcp_f32_e32 v102, v117
	v_rcp_f32_e32 v103, v118
	v_max_f32_e32 v3, 0xda24260, v123
	v_max_f32_e32 v115, 0xda24260, v108
	v_max_f32_e32 v117, 0xda24260, v109
	v_max_f32_e32 v118, 0xda24260, v110
	v_rcp_f32_e32 v104, v119
	v_rcp_f32_e32 v105, v120
	v_rcp_f32_e32 v106, v121
	v_rcp_f32_e32 v107, v122
	v_max_f32_e32 v119, 0xda24260, v111
	v_max_f32_e32 v120, 0xda24260, v112
	v_max_f32_e32 v121, 0xda24260, v113
	v_max_f32_e32 v122, 0xda24260, v114
	v_rcp_f32_e32 v108, v3
	v_rcp_f32_e32 v109, v115
	v_rcp_f32_e32 v110, v117
	v_rcp_f32_e32 v111, v118
	v_rcp_f32_e32 v112, v119
	v_rcp_f32_e32 v113, v120
	v_rcp_f32_e32 v114, v121
	v_rcp_f32_e32 v115, v122
	v_lshlrev_b32_e32 v84, 16, v88
	v_and_b32_e32 v85, 0xffff0000, v88
	v_lshlrev_b32_e32 v86, 16, v89
	v_and_b32_e32 v87, 0xffff0000, v89
	v_lshlrev_b32_e32 v88, 16, v90
	v_and_b32_e32 v89, 0xffff0000, v90
	v_lshlrev_b32_e32 v90, 16, v91
	v_and_b32_e32 v91, 0xffff0000, v91
	s_waitcnt vmcnt(0)
	v_lshlrev_b32_e32 v92, 16, v96
	v_and_b32_e32 v93, 0xffff0000, v96
	v_lshlrev_b32_e32 v94, 16, v97
	v_and_b32_e32 v95, 0xffff0000, v97
	v_pk_mul_f32 v[84:85], v[100:101], v[84:85]
	v_pk_mul_f32 v[86:87], v[102:103], v[86:87]
	v_lshlrev_b32_e32 v96, 16, v98
	v_and_b32_e32 v97, 0xffff0000, v98
	v_lshlrev_b32_e32 v98, 16, v99
	v_and_b32_e32 v99, 0xffff0000, v99
	v_pk_mul_f32 v[88:89], v[104:105], v[88:89]
	v_pk_mul_f32 v[90:91], v[106:107], v[90:91]
	s_waitcnt lgkmcnt(3)
	v_pk_mul_f32 v[68:69], v[68:69], v[84:85]
	v_pk_mul_f32 v[70:71], v[70:71], v[86:87]
	v_pk_mul_f32 v[84:85], v[108:109], v[92:93]
	v_pk_mul_f32 v[86:87], v[110:111], v[94:95]
	s_waitcnt lgkmcnt(2)
	v_pk_mul_f32 v[72:73], v[72:73], v[88:89]
	v_pk_mul_f32 v[74:75], v[74:75], v[90:91]
	v_pk_mul_f32 v[88:89], v[112:113], v[96:97]
	v_pk_mul_f32 v[90:91], v[114:115], v[98:99]
	ds_write_b128 v116, v[68:71]
	ds_write_b128 v116, v[72:75] offset:16
	s_waitcnt lgkmcnt(3)
	v_pk_mul_f32 v[68:69], v[76:77], v[84:85]
	v_pk_mul_f32 v[70:71], v[78:79], v[86:87]
	s_waitcnt lgkmcnt(2)
	v_pk_mul_f32 v[72:73], v[80:81], v[88:89]
	v_pk_mul_f32 v[74:75], v[82:83], v[90:91]
	ds_write_b128 v116, v[68:71] offset:4160
	ds_write_b128 v116, v[72:75] offset:4176
	s_cbranch_scc1 .LBB0_561
	s_waitcnt lgkmcnt(0)
	s_barrier
	ds_read2_b32 v[68:69], v219 offset1:16
	ds_read2_b32 v[2:3], v145 offset0:4 offset1:20
	ds_read2_b32 v[70:71], v144 offset0:8 offset1:24
	ds_read2_b32 v[78:79], v143 offset0:12 offset1:28
	s_andn2_b64 vcc, exec, s[24:25]
	s_waitcnt lgkmcnt(3)
	v_mov_b32_e32 v72, v69
	s_waitcnt lgkmcnt(2)
	v_mov_b32_e32 v69, v2
	v_mov_b32_e32 v73, v3
	s_waitcnt lgkmcnt(1)
	v_mov_b32_e32 v74, v71
	s_waitcnt lgkmcnt(0)
	v_mov_b32_e32 v71, v78
	ds_read2_b32 v[76:77], v142 offset0:64 offset1:80
	ds_read2_b32 v[2:3], v141 offset0:68 offset1:84
	v_mov_b32_e32 v75, v79
	ds_read2_b32 v[78:79], v140 offset0:72 offset1:88
	ds_read2_b32 v[86:87], v139 offset0:76 offset1:92
	s_waitcnt lgkmcnt(3)
	v_mov_b32_e32 v80, v77
	s_waitcnt lgkmcnt(2)
	v_mov_b32_e32 v77, v2
	v_mov_b32_e32 v81, v3
	s_waitcnt lgkmcnt(1)
	v_mov_b32_e32 v82, v79
	s_waitcnt lgkmcnt(0)
	v_mov_b32_e32 v79, v86
	ds_read2_b32 v[84:85], v147 offset0:128 offset1:144
	ds_read2_b32 v[2:3], v138 offset0:132 offset1:148
	v_mov_b32_e32 v83, v87
	ds_read2_b32 v[86:87], v136 offset0:136 offset1:152
	ds_read2_b32 v[94:95], v135 offset0:140 offset1:156
	s_waitcnt lgkmcnt(3)
	v_mov_b32_e32 v88, v85
	s_waitcnt lgkmcnt(2)
	v_mov_b32_e32 v85, v2
	v_mov_b32_e32 v89, v3
	s_waitcnt lgkmcnt(1)
	v_mov_b32_e32 v90, v87
	s_waitcnt lgkmcnt(0)
	v_mov_b32_e32 v87, v94
	ds_read2_b32 v[92:93], v146 offset0:192 offset1:208
	ds_read2_b32 v[2:3], v134 offset0:196 offset1:212
	v_mov_b32_e32 v91, v95
	ds_read2_b32 v[94:95], v133 offset0:200 offset1:216
	ds_read2_b32 v[102:103], v132 offset0:204 offset1:220
	s_waitcnt lgkmcnt(3)
	v_mov_b32_e32 v96, v93
	s_waitcnt lgkmcnt(2)
	v_mov_b32_e32 v93, v2
	v_mov_b32_e32 v97, v3
	s_waitcnt lgkmcnt(1)
	v_mov_b32_e32 v98, v95
	s_waitcnt lgkmcnt(0)
	v_mov_b32_e32 v95, v102
	ds_read2_b32 v[100:101], v219 offset0:128 offset1:144
	ds_read2_b32 v[2:3], v145 offset0:132 offset1:148
	v_mov_b32_e32 v99, v103
	ds_read2_b32 v[102:103], v144 offset0:136 offset1:152
	ds_read2_b32 v[110:111], v143 offset0:140 offset1:156
	s_waitcnt lgkmcnt(3)
	v_mov_b32_e32 v104, v101
	s_waitcnt lgkmcnt(2)
	v_mov_b32_e32 v101, v2
	v_mov_b32_e32 v105, v3
	s_waitcnt lgkmcnt(1)
	v_mov_b32_e32 v106, v103
	s_waitcnt lgkmcnt(0)
	v_mov_b32_e32 v103, v110
	ds_read2_b32 v[108:109], v142 offset0:192 offset1:208
	ds_read2_b32 v[2:3], v141 offset0:196 offset1:212
	v_mov_b32_e32 v107, v111
	ds_read2_b32 v[110:111], v140 offset0:200 offset1:216
	ds_read2_b32 v[118:119], v139 offset0:204 offset1:220
	s_waitcnt lgkmcnt(3)
	v_mov_b32_e32 v112, v109
	s_waitcnt lgkmcnt(2)
	v_mov_b32_e32 v109, v2
	v_mov_b32_e32 v113, v3
	s_waitcnt lgkmcnt(1)
	v_mov_b32_e32 v114, v111
	s_waitcnt lgkmcnt(0)
	v_mov_b32_e32 v111, v118
	ds_read2_b32 v[116:117], v138 offset1:16
	ds_read2_b32 v[2:3], v136 offset0:4 offset1:20
	v_mov_b32_e32 v115, v119
	ds_read2_b32 v[118:119], v135 offset0:8 offset1:24
	ds_read2_b32 v[126:127], v137 offset0:12 offset1:28
	s_waitcnt lgkmcnt(3)
	v_mov_b32_e32 v120, v117
	s_waitcnt lgkmcnt(2)
	v_mov_b32_e32 v117, v2
	v_mov_b32_e32 v121, v3
	s_waitcnt lgkmcnt(1)
	v_mov_b32_e32 v122, v119
	s_waitcnt lgkmcnt(0)
	v_mov_b32_e32 v119, v126
	ds_read2_b32 v[124:125], v134 offset0:64 offset1:80
	ds_read2_b32 v[2:3], v133 offset0:68 offset1:84
	v_mov_b32_e32 v123, v127
	ds_read2_b32 v[126:127], v132 offset0:72 offset1:88
	ds_read2_b32 v[148:149], v0 offset0:76 offset1:92
	s_waitcnt lgkmcnt(3)
	v_mov_b32_e32 v128, v125
	s_waitcnt lgkmcnt(2)
	v_mov_b32_e32 v125, v2
	v_mov_b32_e32 v129, v3
	s_waitcnt lgkmcnt(1)
	v_mov_b32_e32 v130, v127
	s_waitcnt lgkmcnt(0)
	v_mov_b32_e32 v127, v148
	v_mov_b32_e32 v131, v149
	s_cbranch_vccnz .LBB0_533
	s_mov_b32 s2, 0
	v_mov_b32_e32 v2, v226
	s_barrier
	ds_write2_b32 v219, v8, v4 offset1:16
	ds_write2_b32 v145, v9, v5 offset0:4 offset1:20
	ds_write2_b32 v144, v10, v6 offset0:8 offset1:24
	ds_write2_b32 v143, v11, v7 offset0:12 offset1:28
	ds_write2_b32 v142, v16, v12 offset0:64 offset1:80
	ds_write2_b32 v141, v17, v13 offset0:68 offset1:84
	ds_write2_b32 v140, v18, v14 offset0:72 offset1:88
	ds_write2_b32 v139, v19, v15 offset0:76 offset1:92
	ds_write2_b32 v147, v24, v20 offset0:128 offset1:144
	ds_write2_b32 v138, v25, v21 offset0:132 offset1:148
	ds_write2_b32 v136, v26, v22 offset0:136 offset1:152
	ds_write2_b32 v135, v27, v23 offset0:140 offset1:156
	ds_write2_b32 v146, v32, v28 offset0:192 offset1:208
	ds_write2_b32 v134, v33, v29 offset0:196 offset1:212
	ds_write2_b32 v133, v34, v30 offset0:200 offset1:216
	ds_write2_b32 v132, v35, v31 offset0:204 offset1:220
	ds_write2_b32 v219, v40, v36 offset0:128 offset1:144
	ds_write2_b32 v145, v41, v37 offset0:132 offset1:148
	ds_write2_b32 v144, v42, v38 offset0:136 offset1:152
	ds_write2_b32 v143, v43, v39 offset0:140 offset1:156
	ds_write2_b32 v142, v48, v44 offset0:192 offset1:208
	ds_write2_b32 v141, v49, v45 offset0:196 offset1:212
	ds_write2_b32 v140, v50, v46 offset0:200 offset1:216
	ds_write2_b32 v139, v51, v47 offset0:204 offset1:220
	ds_write2_b32 v138, v56, v52 offset1:16
	ds_write2_b32 v136, v57, v53 offset0:4 offset1:20
	ds_write2_b32 v135, v58, v54 offset0:8 offset1:24
	ds_write2_b32 v137, v59, v55 offset0:12 offset1:28
	ds_write2_b32 v134, v64, v60 offset0:64 offset1:80
	ds_write2_b32 v133, v65, v61 offset0:68 offset1:84
	ds_write2_b32 v132, v66, v62 offset0:72 offset1:88
	ds_write2_b32 v0, v67, v63 offset0:76 offset1:92
	s_waitcnt lgkmcnt(0)
	s_barrier
.LBB0_564:
	v_add_u32_e32 v20, -4, v2
	v_ashrrev_i32_e32 v3, 31, v2
	v_ashrrev_i32_e32 v21, 31, v20
	v_lshlrev_b64 v[22:23], 10, v[2:3]
	v_lshlrev_b64 v[20:21], 10, v[20:21]
	v_lshl_add_u64 v[22:23], v[22:23], 0, v[198:199]
	v_lshl_add_u64 v[20:21], v[20:21], 0, v[198:199]
	v_lshlrev_b64 v[22:23], 1, v[22:23]
	v_add_u32_e32 v52, s2, v221
	v_lshlrev_b64 v[28:29], 1, v[20:21]
	v_lshl_add_u64 v[24:25], s[6:7], 0, v[22:23]
	v_lshl_add_u64 v[20:21], s[8:9], 0, v[22:23]
	ds_read_b128 v[4:7], v52
	ds_read_b128 v[8:11], v52 offset:16
	ds_read_b128 v[12:15], v52 offset:4160
	ds_read_b128 v[16:19], v52 offset:4176
	global_load_dwordx4 v[20:23], v[20:21], off
	s_nop 0
	global_load_dwordx4 v[24:27], v[24:25], off nt
	v_lshl_add_u64 v[32:33], s[6:7], 0, v[28:29]
	v_lshl_add_u64 v[28:29], s[8:9], 0, v[28:29]
	global_load_dwordx4 v[28:31], v[28:29], off
	s_nop 0
	global_load_dwordx4 v[32:35], v[32:33], off nt
	s_addk_i32 s2, 0x2080
	v_add_u32_e32 v2, 8, v2
	s_cmpk_lg_u32 s2, 0x8200
	s_waitcnt vmcnt(3)
	v_lshlrev_b32_e32 v3, 16, v20
	v_and_b32_e32 v36, 0xffff0000, v20
	v_lshlrev_b32_e32 v37, 16, v21
	v_and_b32_e32 v38, 0xffff0000, v21
	v_lshlrev_b32_e32 v39, 16, v22
	v_and_b32_e32 v40, 0xffff0000, v22
	v_lshlrev_b32_e32 v41, 16, v23
	v_and_b32_e32 v42, 0xffff0000, v23
	s_waitcnt vmcnt(1)
	v_lshlrev_b32_e32 v43, 16, v28
	v_and_b32_e32 v44, 0xffff0000, v28
	v_lshlrev_b32_e32 v45, 16, v29
	v_and_b32_e32 v46, 0xffff0000, v29
	v_lshlrev_b32_e32 v47, 16, v30
	v_and_b32_e32 v48, 0xffff0000, v30
	v_lshlrev_b32_e32 v49, 16, v31
	v_and_b32_e32 v50, 0xffff0000, v31
	v_max_f32_e32 v3, v3, v3
	v_max_f32_e32 v36, v36, v36
	v_max_f32_e32 v37, v37, v37
	v_max_f32_e32 v38, v38, v38
	v_max_f32_e32 v39, v39, v39
	v_max_f32_e32 v40, v40, v40
	v_max_f32_e32 v41, v41, v41
	v_max_f32_e32 v42, v42, v42
	v_max_f32_e32 v43, v43, v43
	v_max_f32_e32 v44, v44, v44
	v_max_f32_e32 v45, v45, v45
	v_max_f32_e32 v46, v46, v46
	v_max_f32_e32 v47, v47, v47
	v_max_f32_e32 v48, v48, v48
	v_max_f32_e32 v49, v49, v49
	v_max_f32_e32 v50, v50, v50
	v_max_f32_e32 v3, 0xda24260, v3
	v_max_f32_e32 v51, 0xda24260, v36
	v_max_f32_e32 v53, 0xda24260, v37
	v_max_f32_e32 v54, 0xda24260, v38
	v_max_f32_e32 v55, 0xda24260, v39
	v_max_f32_e32 v56, 0xda24260, v40
	v_max_f32_e32 v57, 0xda24260, v41
	v_max_f32_e32 v58, 0xda24260, v42
	v_max_f32_e32 v59, 0xda24260, v43
	v_max_f32_e32 v60, 0xda24260, v44
	v_max_f32_e32 v61, 0xda24260, v45
	v_max_f32_e32 v62, 0xda24260, v46
	v_max_f32_e32 v63, 0xda24260, v47
	v_max_f32_e32 v64, 0xda24260, v48
	v_max_f32_e32 v65, 0xda24260, v49
	v_max_f32_e32 v66, 0xda24260, v50
	v_rcp_f32_e32 v36, v3
	v_rcp_f32_e32 v37, v51
	v_rcp_f32_e32 v38, v53
	v_rcp_f32_e32 v39, v54
	v_rcp_f32_e32 v40, v55
	v_rcp_f32_e32 v41, v56
	v_rcp_f32_e32 v42, v57
	v_rcp_f32_e32 v43, v58
	v_rcp_f32_e32 v44, v59
	v_rcp_f32_e32 v45, v60
	v_rcp_f32_e32 v46, v61
	v_rcp_f32_e32 v47, v62
	v_rcp_f32_e32 v48, v63
	v_rcp_f32_e32 v49, v64
	v_rcp_f32_e32 v50, v65
	v_rcp_f32_e32 v51, v66
	v_lshlrev_b32_e32 v20, 16, v24
	v_and_b32_e32 v21, 0xffff0000, v24
	v_lshlrev_b32_e32 v22, 16, v25
	v_and_b32_e32 v23, 0xffff0000, v25
	v_lshlrev_b32_e32 v24, 16, v26
	v_and_b32_e32 v25, 0xffff0000, v26
	v_lshlrev_b32_e32 v26, 16, v27
	v_and_b32_e32 v27, 0xffff0000, v27
	s_waitcnt vmcnt(0)
	v_lshlrev_b32_e32 v28, 16, v32
	v_and_b32_e32 v29, 0xffff0000, v32
	v_lshlrev_b32_e32 v30, 16, v33
	v_and_b32_e32 v31, 0xffff0000, v33
	v_lshlrev_b32_e32 v32, 16, v34
	v_and_b32_e32 v33, 0xffff0000, v34
	v_lshlrev_b32_e32 v34, 16, v35
	v_and_b32_e32 v35, 0xffff0000, v35
	v_pk_mul_f32 v[20:21], v[36:37], v[20:21]
	v_pk_mul_f32 v[22:23], v[38:39], v[22:23]
	v_pk_mul_f32 v[24:25], v[40:41], v[24:25]
	v_pk_mul_f32 v[26:27], v[42:43], v[26:27]
	v_pk_mul_f32 v[28:29], v[44:45], v[28:29]
	v_pk_mul_f32 v[30:31], v[46:47], v[30:31]
	v_pk_mul_f32 v[32:33], v[48:49], v[32:33]
	v_pk_mul_f32 v[34:35], v[50:51], v[34:35]
	s_waitcnt lgkmcnt(1)
	v_pk_mul_f32 v[12:13], v[12:13], v[20:21]
	v_pk_mul_f32 v[14:15], v[14:15], v[22:23]
	s_waitcnt lgkmcnt(0)
	v_pk_mul_f32 v[16:17], v[16:17], v[24:25]
	v_pk_mul_f32 v[18:19], v[18:19], v[26:27]
	v_pk_mul_f32 v[4:5], v[4:5], v[28:29]
	v_pk_mul_f32 v[6:7], v[6:7], v[30:31]
	v_pk_mul_f32 v[8:9], v[8:9], v[32:33]
	v_pk_mul_f32 v[10:11], v[10:11], v[34:35]
	ds_write_b128 v52, v[12:15] offset:4160
	ds_write_b128 v52, v[16:19] offset:4176
	ds_write_b128 v52, v[4:7]
	ds_write_b128 v52, v[8:11] offset:16
	s_cbranch_scc1 .LBB0_564
	s_waitcnt lgkmcnt(0)
	s_barrier
	ds_read2_b32 v[2:3], v219 offset1:16
	ds_read2_b32 v[4:5], v145 offset0:4 offset1:20
	ds_read2_b32 v[16:17], v144 offset0:8 offset1:24
	ds_read2_b32 v[6:7], v143 offset0:12 offset1:28
	s_waitcnt lgkmcnt(3)
	v_mov_b32_e32 v8, v2
	s_waitcnt lgkmcnt(2)
	v_mov_b32_e32 v9, v4
	v_mov_b32_e32 v4, v3
	ds_read2_b32 v[2:3], v142 offset0:64 offset1:80
	ds_read2_b32 v[12:13], v141 offset0:68 offset1:84
	ds_read2_b32 v[24:25], v140 offset0:72 offset1:88
	ds_read2_b32 v[14:15], v139 offset0:76 offset1:92
	s_waitcnt lgkmcnt(5)
	v_mov_b32_e32 v10, v16
	s_waitcnt lgkmcnt(4)
	v_mov_b32_e32 v11, v6
	v_mov_b32_e32 v6, v17
	s_waitcnt lgkmcnt(3)
	v_mov_b32_e32 v16, v2
	s_waitcnt lgkmcnt(2)
	v_mov_b32_e32 v17, v12
	v_mov_b32_e32 v12, v3
	ds_read2_b32 v[2:3], v147 offset0:128 offset1:144
	ds_read2_b32 v[20:21], v138 offset0:132 offset1:148
	ds_read2_b32 v[32:33], v136 offset0:136 offset1:152
	ds_read2_b32 v[22:23], v135 offset0:140 offset1:156
	s_waitcnt lgkmcnt(5)
	v_mov_b32_e32 v18, v24
	s_waitcnt lgkmcnt(4)
	v_mov_b32_e32 v19, v14
	v_mov_b32_e32 v14, v25
	s_waitcnt lgkmcnt(3)
	v_mov_b32_e32 v24, v2
	s_waitcnt lgkmcnt(2)
	v_mov_b32_e32 v25, v20
	v_mov_b32_e32 v20, v3
	ds_read2_b32 v[2:3], v146 offset0:192 offset1:208
	ds_read2_b32 v[28:29], v134 offset0:196 offset1:212
	ds_read2_b32 v[40:41], v133 offset0:200 offset1:216
	ds_read2_b32 v[30:31], v132 offset0:204 offset1:220
	s_waitcnt lgkmcnt(5)
	v_mov_b32_e32 v26, v32
	s_waitcnt lgkmcnt(4)
	v_mov_b32_e32 v27, v22
	v_mov_b32_e32 v22, v33
	s_waitcnt lgkmcnt(3)
	v_mov_b32_e32 v32, v2
	s_waitcnt lgkmcnt(2)
	v_mov_b32_e32 v33, v28
	v_mov_b32_e32 v28, v3
	ds_read2_b32 v[2:3], v219 offset0:128 offset1:144
	ds_read2_b32 v[36:37], v145 offset0:132 offset1:148
	ds_read2_b32 v[48:49], v144 offset0:136 offset1:152
	ds_read2_b32 v[38:39], v143 offset0:140 offset1:156
	s_waitcnt lgkmcnt(5)
	v_mov_b32_e32 v34, v40
	s_waitcnt lgkmcnt(4)
	v_mov_b32_e32 v35, v30
	v_mov_b32_e32 v30, v41
	s_waitcnt lgkmcnt(3)
	v_mov_b32_e32 v40, v2
	s_waitcnt lgkmcnt(2)
	v_mov_b32_e32 v41, v36
	v_mov_b32_e32 v36, v3
	ds_read2_b32 v[2:3], v142 offset0:192 offset1:208
	ds_read2_b32 v[44:45], v141 offset0:196 offset1:212
	ds_read2_b32 v[56:57], v140 offset0:200 offset1:216
	ds_read2_b32 v[46:47], v139 offset0:204 offset1:220
	s_waitcnt lgkmcnt(5)
	v_mov_b32_e32 v42, v48
	s_waitcnt lgkmcnt(4)
	v_mov_b32_e32 v43, v38
	v_mov_b32_e32 v38, v49
	s_waitcnt lgkmcnt(3)
	v_mov_b32_e32 v48, v2
	s_waitcnt lgkmcnt(2)
	v_mov_b32_e32 v49, v44
	v_mov_b32_e32 v44, v3
	ds_read2_b32 v[2:3], v138 offset1:16
	ds_read2_b32 v[52:53], v136 offset0:4 offset1:20
	ds_read2_b32 v[64:65], v135 offset0:8 offset1:24
	ds_read2_b32 v[54:55], v137 offset0:12 offset1:28
	s_waitcnt lgkmcnt(5)
	v_mov_b32_e32 v50, v56
	s_waitcnt lgkmcnt(4)
	v_mov_b32_e32 v51, v46
	v_mov_b32_e32 v46, v57
	s_waitcnt lgkmcnt(3)
	v_mov_b32_e32 v56, v2
	s_waitcnt lgkmcnt(2)
	v_mov_b32_e32 v57, v52
	v_mov_b32_e32 v52, v3
	ds_read2_b32 v[2:3], v134 offset0:64 offset1:80
	ds_read2_b32 v[60:61], v133 offset0:68 offset1:84
	ds_read2_b32 v[132:133], v132 offset0:72 offset1:88
	ds_read2_b32 v[62:63], v0 offset0:76 offset1:92
	s_waitcnt lgkmcnt(5)
	v_mov_b32_e32 v58, v64
	s_waitcnt lgkmcnt(4)
	v_mov_b32_e32 v59, v54
	v_mov_b32_e32 v54, v65
	s_waitcnt lgkmcnt(3)
	v_mov_b32_e32 v64, v2
	s_waitcnt lgkmcnt(2)
	v_mov_b32_e32 v65, v60
	s_waitcnt lgkmcnt(1)
	v_mov_b32_e32 v66, v132
	s_waitcnt lgkmcnt(0)
	v_mov_b32_e32 v67, v62
	v_mov_b32_e32 v60, v3
	v_mov_b32_e32 v62, v133
	s_branch .LBB0_533
